# D1 chunk prep: the ninth-round 512 sample chunks dealt two per workgroup (waves 0,1 of all 256) instead of to all waves of the first 64 workgroups
# speedup vs baseline: 1.0072x; 1.0072x over previous
; __device__ __forceinline__ float bf2f(bf16_t b) { return __uint_as_float((unsigned)b << 16); }
; __device__ __forceinline__ void raw_load(Raw& x, const char* rec, int lane) {
;     const int fr = lane & 15, fq = lane >> 4;
; #pragma unroll
;     for (int t = 0; t < 16; ++t) {
;         const float* rp = (const float*)(rec + (size_t)t * REC) + lane; const bf16_t* hp = (const bf16_t*)(rec + (size_t)t * REC + 768) + lane;
;         x.w[t] = rp[0]; x.kk[t] = rp[64]; x.b[t] = rp[128]; x.r[t] = bf2f(hp[0]); x.k[t] = bf2f(hp[64]);
;     }
; #pragma unroll
;     for (int vt = 0; vt < 4; ++vt)
; #pragma unroll
;         for (int e = 0; e < 4; ++e) x.v[vt * 4 + e] = bf2f(*(const bf16_t*)(rec + (size_t)(4 * fq + e) * REC + 1024 + (16 * vt + fr) * 2));
; }
.LBB0_674:
	v_lshlrev_b32_e32 v2, 2, v20
	v_lshl_add_u64 v[12:13], s[42:43], 0, v[2:3]
	global_load_dword v6, v2, s[42:43]
	global_load_dword v36, v2, s[42:43] offset:256
	global_load_dword v4, v2, s[42:43] offset:512
	v_lshlrev_b32_e32 v2, 1, v20
	v_lshl_add_u64 v[44:45], s[42:43], 0, v[2:3]
	s_mov_b64 vcc, 0x1080
	v_lshl_add_u64 v[14:15], v[44:45], 0, vcc
	s_mov_b64 vcc, 0x1200
	v_lshl_add_u64 v[16:17], v[12:13], 0, vcc
	s_mov_b64 vcc, 0x1500
	s_movk_i32 s51, 0x1000
	v_lshl_add_u64 v[18:19], v[44:45], 0, vcc
	v_add_co_u32_e32 v8, vcc, s51, v12
	s_movk_i32 s52, 0x2000
	s_nop 0
	v_addc_co_u32_e32 v9, vcc, 0, v13, vcc
	s_mov_b64 vcc, 0x1680
	s_nop 0
	v_lshl_add_u64 v[48:49], v[12:13], 0, vcc
	s_mov_b64 vcc, 0x1980
	v_lshl_add_u64 v[46:47], v[44:45], 0, vcc
	s_mov_b64 vcc, 0x1b00
	v_lshl_add_u64 v[52:53], v[12:13], 0, vcc
	s_mov_b64 vcc, 0x1e00
	v_lshl_add_u64 v[50:51], v[44:45], 0, vcc
	s_mov_b64 vcc, 0x1f80
	v_lshl_add_u64 v[62:63], v[12:13], 0, vcc
	s_mov_b64 vcc, 0x2280
	v_lshl_add_u64 v[66:67], v[44:45], 0, vcc
	s_mov_b64 vcc, 0x2400
	v_lshl_add_u64 v[54:55], v[12:13], 0, vcc
	s_mov_b64 vcc, 0x2700
	v_lshl_add_u64 v[60:61], v[44:45], 0, vcc
	v_add_co_u32_e32 v10, vcc, s52, v12
	v_lshl_add_u64 v[74:75], v[12:13], 0, v[38:39]
	s_nop 0
	v_addc_co_u32_e32 v11, vcc, 0, v13, vcc
	s_mov_b64 vcc, 0x2880
	s_nop 0
	v_lshl_add_u64 v[56:57], v[12:13], 0, vcc
	s_mov_b64 vcc, 0x2b80
	v_lshl_add_u64 v[80:81], v[44:45], 0, vcc
	s_mov_b64 vcc, 0x2d00
	v_lshl_add_u64 v[76:77], v[74:75], 0, v[22:23]
	v_lshl_add_u64 v[84:85], v[12:13], 0, vcc
	s_mov_b64 vcc, 0x3000
	global_load_dword v7, v[76:77], off offset:1152
	global_load_dword v2, v[76:77], off offset:1408
	global_load_dword v136, v[8:9], off offset:512
	global_load_dword v58, v[16:17], off offset:256
	global_load_dword v135, v[8:9], off offset:1664
	global_load_dword v59, v[48:49], off offset:256
	global_load_dword v134, v[8:9], off offset:2816
	s_nop 0
	global_load_dword v8, v[8:9], off offset:3968
	s_nop 0
	global_load_dword v70, v[52:53], off offset:256
	global_load_dword v71, v[62:63], off offset:256
	global_load_dword v140, v[10:11], off offset:1024
	global_load_dword v78, v[54:55], off offset:256
	global_load_dword v138, v[10:11], off offset:2176
	global_load_dword v79, v[56:57], off offset:256
	global_load_dword v9, v[56:57], off offset:512
	global_load_dword v137, v[10:11], off offset:3328
	v_lshl_add_u64 v[56:57], s[42:43], 0, v[28:29]
	v_lshl_add_u64 v[82:83], v[44:45], 0, vcc
	s_mov_b64 vcc, 0x3180
	v_lshl_add_u64 v[88:89], v[76:77], 0, v[38:39]
	v_lshl_add_u64 v[10:11], s[42:43], 0, v[26:27]
	v_lshl_add_u64 v[92:93], v[56:57], 0, v[24:25]
	v_lshl_add_u64 v[56:57], v[56:57], 0, v[30:31]
	s_movk_i32 s53, 0x3000
	v_lshl_add_u64 v[86:87], v[12:13], 0, vcc
	v_lshl_add_u64 v[68:69], v[88:89], 0, v[22:23]
	v_lshl_add_u64 v[90:91], v[10:11], 0, v[24:25]
	global_load_ushort v5, v[92:93], off offset:1024
	global_load_ushort v132, v[90:91], off offset:1024
	global_load_ushort v133, v[90:91], off offset:2176
	global_load_ushort v139, v[90:91], off offset:3328
	global_load_ushort v130, v[90:91], off offset:1056
	global_load_ushort v131, v[90:91], off offset:2208
	global_load_ushort v141, v[90:91], off offset:3360
	global_load_ushort v142, v[90:91], off offset:2240
	global_load_ushort v145, v[90:91], off offset:1088
	v_lshl_add_u64 v[10:11], v[10:11], 0, v[30:31]
	global_load_ushort v151, v[92:93], off offset:1056
	global_load_ushort v146, v[92:93], off offset:1088
	global_load_ushort v147, v[10:11], off offset:1024
	global_load_ushort v148, v[10:11], off offset:2176
	global_load_ushort v149, v[10:11], off offset:3328
	global_load_ushort v150, v[56:57], off offset:1024
	global_load_ushort v152, v[90:91], off offset:3392
	v_add_co_u32_e32 v56, vcc, s53, v12
	s_mov_b64 s[42:43], 0x3480
	s_nop 0
	v_addc_co_u32_e32 v57, vcc, 0, v13, vcc
	global_load_dword v102, v[84:85], off offset:256
	global_load_dword v143, v[56:57], off offset:384
	global_load_dword v103, v[86:87], off offset:256
	global_load_dword v144, v[68:69], off offset:2304
	global_load_ushort v154, v[74:75], off offset:768
	global_load_ushort v153, v[88:89], off offset:1920
	v_lshl_add_u64 v[96:97], v[44:45], 0, s[42:43]
	s_mov_b64 s[42:43], 0x3600
	v_add_co_u32_e32 v94, vcc, s51, v44
	v_lshl_add_u64 v[64:65], v[68:69], 0, v[38:39]
	v_lshl_add_u64 v[10:11], v[12:13], 0, s[42:43]
	s_mov_b64 s[42:43], 0x3900
	v_addc_co_u32_e32 v95, vcc, 0, v45, vcc
	v_lshl_add_u64 v[72:73], v[64:65], 0, v[22:23]
	v_lshl_add_u64 v[90:91], v[44:45], 0, s[42:43]
	s_mov_b64 s[42:43], 0x3a80
	global_load_ushort v159, v[94:95], off offset:128
	global_load_dword v92, v[68:69], off offset:2560
	global_load_dword v157, v[72:73], off offset:3456
	global_load_dword v93, v[72:73], off offset:3712
	global_load_ushort v158, v[64:65], off offset:3072
	s_mul_i32 s10, s39, 0x3c00
	s_mul_hi_u32 s39, s38, 0x3c00
	v_lshl_add_u64 v[160:161], v[12:13], 0, s[42:43]
	s_mov_b64 s[42:43], 0x3d80
	s_add_i32 s39, s39, s10
	s_mul_i32 s10, s38, 0x3c00
	v_readlane_b32 s38, v254, 60
	v_lshl_add_u64 v[98:99], v[44:45], 0, s[42:43]
	s_mov_b64 s[42:43], 0x3f00
	global_load_ushort v172, v[94:95], off offset:1280
	global_load_ushort v173, v[94:95], off offset:2432
	global_load_dword v156, v[56:57], off offset:1536
	global_load_dword v106, v[10:11], off offset:256
	s_nop 0
	global_load_dword v10, v[10:11], off offset:512
	s_nop 0
	global_load_dword v155, v[56:57], off offset:2688
	global_load_dword v107, v[160:161], off offset:256
	global_load_dword v11, v[160:161], off offset:512
	global_load_ushort v129, v[90:91], off offset:128
	global_load_dword v174, v[56:57], off offset:3840
	v_add_co_u32_e32 v56, vcc, s52, v44
	s_add_u32 s38, s38, s10
	v_readlane_b32 s10, v254, 62
	v_lshl_add_u64 v[100:101], v[12:13], 0, s[42:43]
	s_mov_b64 s[42:43], 0x4200
	v_addc_co_u32_e32 v57, vcc, 0, v45, vcc
	global_load_ushort v90, v[94:95], off offset:3584
	global_load_ushort v91, v[56:57], off offset:640
	s_addc_u32 s39, s10, s39
	v_lshl_add_u64 v[104:105], v[44:45], 0, s[42:43]
	s_mov_b64 s[42:43], 0x4380
	s_movk_i32 s10, 0x4000
	v_lshl_add_u64 v[160:161], v[12:13], 0, s[42:43]
	v_add_co_u32_e32 v12, vcc, s10, v12
	s_mov_b64 s[42:43], 0x4680
	s_nop 0
	v_addc_co_u32_e32 v13, vcc, 0, v13, vcc
	global_load_dword v164, v[100:101], off offset:256
	global_load_dword v175, v[12:13], off offset:896
	global_load_dword v165, v[160:161], off offset:256
	global_load_ushort v180, v[56:57], off offset:1792
	global_load_ushort v181, v[56:57], off offset:2944
	v_add_co_u32_e32 v12, vcc, s53, v44
	v_lshl_add_u64 v[162:163], v[44:45], 0, s[42:43]
	s_nop 0
	v_addc_co_u32_e32 v13, vcc, 0, v45, vcc
	global_load_ushort v186, v[12:13], off offset:1152
	global_load_ushort v187, v[12:13], off
	v_add_co_u32_e32 v44, vcc, s10, v44
	s_waitcnt vmcnt(0)
; __device__ __forceinline__ s16x4 pack4(const f32x4& a) { u32x2 w; w.x = cpk(a.x, a.y); w.y = cpk(a.z, a.w); return __builtin_bit_cast(s16x4, w); }
; __device__ __forceinline__ void precompute(const char* rec, char* out, LAS char* wl, int lane) {
;     ...
; #pragma unroll
;     for (int t = 0; t < 16; ++t) {
;         const float Pm1 = P; P *= x.w[t]; const float ip = __builtin_amdgcn_rcpf(P);
;         At[t] = -x.kk[t] * Pm1; Rt[t] = x.r[t] * P; Bt[t] = x.b[t] * ip; Kt[t] = x.k[t] * ip;
;     }
;     const float P15 = P;
; #pragma unroll
;     for (int vt = 0; vt < 4; ++vt) *(s16x4*)(out + O_VB + vt * 512 + lane * 8) = pack4((f32x4){x.v[vt * 4 + 0], x.v[vt * 4 + 1], x.v[vt * 4 + 2], x.v[vt * 4 + 3]});
;     *(float*)(out + O_P + lane * 4) = P15;
	v_rcp_f32_e32 v56, v6
	v_addc_co_u32_e32 v45, vcc, 0, v45, vcc
	s_mov_b64 s[42:43], 0x3200
	v_mul_f32_e32 v7, v6, v7
	v_rcp_f32_e32 v57, v7
	s_mul_hi_i32 s10, s19, 0x4800
	v_lshlrev_b32_e32 v179, 16, v5
	v_lshlrev_b32_e32 v176, 16, v132
	v_lshlrev_b32_e32 v177, 16, v133
	v_lshlrev_b32_e32 v178, 16, v139
	v_lshlrev_b32_e32 v182, 16, v130
	v_lshlrev_b32_e32 v183, 16, v131
	global_load_dword v5, v[76:77], off offset:1664
	global_load_ushort v130, v[88:89], off offset:2048
	global_load_ushort v131, v[74:75], off offset:896
	global_load_ushort v194, v[12:13], off offset:2304
	global_load_ushort v195, v[12:13], off offset:3456
	v_lshlrev_b32_e32 v184, 16, v141
	v_xor_b32_e32 v141, 0x80000000, v36
	v_lshlrev_b32_e32 v185, 16, v142
	v_mul_f32_e64 v142, v6, -v2
	v_lshlrev_b32_e32 v151, 16, v151
	v_lshlrev_b32_e32 v145, 16, v145
	v_lshlrev_b32_e32 v152, 16, v152
	v_lshlrev_b32_e32 v12, 16, v154
	v_lshlrev_b32_e32 v13, 16, v153
	global_load_ushort v153, v[44:45], off offset:512
	global_load_ushort v154, v[44:45], off offset:1664
	global_load_dword v94, v[68:69], off offset:2816
	global_load_dword v95, v[72:73], off offset:3968
	global_load_ushort v133, v[14:15], off offset:128
	global_load_ushort v132, v[64:65], off offset:3200
	v_mul_f32_e32 v15, v7, v144
	v_mov_b32_e32 v14, v7
	v_pk_mul_f32 v[12:13], v[6:7], v[12:13]
	v_mov_b32_e32 v64, v15
	v_rcp_f32_e32 v68, v15
	v_lshlrev_b32_e32 v146, 16, v146
	v_lshlrev_b32_e32 v45, 16, v159
	v_lshlrev_b32_e32 v147, 16, v147
	v_mul_f32_e32 v65, v15, v157
	v_pk_mul_f32 v[72:73], v[14:15], v[92:93] neg_lo:[0,1] neg_hi:[0,1]
	global_load_dword v92, v[16:17], off offset:512
	global_load_ushort v7, v[18:19], off offset:128
	v_lshlrev_b32_e32 v44, 16, v158
	v_mul_f32_e32 v17, v65, v136
	v_pk_mul_f32 v[14:15], v[64:65], v[44:45]
	v_lshlrev_b32_e32 v45, 16, v173
	v_lshlrev_b32_e32 v44, 16, v172
	v_mov_b32_e32 v16, v65
	v_mul_f32_e32 v19, v17, v135
	v_mov_b32_e32 v18, v17
	v_rcp_f32_e32 v64, v17
	v_pk_mul_f32 v[74:75], v[16:17], v[58:59] neg_lo:[0,1] neg_hi:[0,1]
	v_pk_mul_f32 v[16:17], v[18:19], v[44:45]
	v_mul_f32_e32 v89, v19, v134
	v_rcp_f32_e32 v69, v65
	v_rcp_f32_e32 v65, v19
	v_mov_b32_e32 v88, v19
	v_pk_mul_f32 v[76:77], v[88:89], v[70:71] neg_lo:[0,1] neg_hi:[0,1]
	v_rcp_f32_e32 v58, v89
	v_lshlrev_b32_e32 v44, 16, v90
	v_lshlrev_b32_e32 v45, 16, v91
	global_load_dword v93, v[48:49], off offset:512
	global_load_dword v90, v[52:53], off offset:512
	global_load_dword v91, v[62:63], off offset:512
	global_load_ushort v136, v[66:67], off offset:128
	global_load_ushort v135, v[50:51], off offset:128
	global_load_ushort v139, v[46:47], off offset:128
	v_mul_f32_e32 v47, v89, v8
	v_mov_b32_e32 v46, v89
	v_mul_f32_e32 v49, v47, v140
	v_rcp_f32_e32 v59, v47
	v_pk_mul_f32 v[18:19], v[46:47], v[44:45]
	v_mov_b32_e32 v48, v47
	v_mul_f32_e32 v47, v49, v138
	v_mov_b32_e32 v46, v49
	v_mul_f32_e32 v51, v47, v137
	v_lshlrev_b32_e32 v44, 16, v180
	v_lshlrev_b32_e32 v45, 16, v181
	v_rcp_f32_e32 v70, v49
	v_pk_mul_f32 v[78:79], v[48:49], v[78:79] neg_lo:[0,1] neg_hi:[0,1]
	v_rcp_f32_e32 v71, v47
	v_pk_mul_f32 v[48:49], v[46:47], v[44:45]
	v_mov_b32_e32 v50, v47
	v_mul_f32_e32 v47, v51, v143
	v_lshlrev_b32_e32 v45, 16, v186
	v_lshlrev_b32_e32 v44, 16, v187
	v_mov_b32_e32 v46, v51
	v_mul_f32_e32 v53, v47, v156
	global_load_dword v8, v[54:55], off offset:512
	global_load_ushort v134, v[60:61], off offset:128
	v_rcp_f32_e32 v62, v51
	global_load_dword v88, v[84:85], off offset:512
	global_load_dword v89, v[86:87], off offset:512
	global_load_ushort v138, v[96:97], off offset:128
	global_load_ushort v137, v[82:83], off offset:128
	global_load_ushort v140, v[80:81], off offset:128
	v_pk_mul_f32 v[80:81], v[50:51], v[102:103] neg_lo:[0,1] neg_hi:[0,1]
	v_rcp_f32_e32 v63, v47
	v_pk_mul_f32 v[50:51], v[46:47], v[44:45]
	v_mov_b32_e32 v52, v47
	v_mul_f32_e32 v47, v53, v155
	v_mov_b32_e32 v46, v53
	v_mul_f32_e32 v55, v47, v174
	v_rcp_f32_e32 v66, v53
	v_pk_mul_f32 v[82:83], v[52:53], v[106:107] neg_lo:[0,1] neg_hi:[0,1]
	v_mul_f32_e32 v97, v55, v175
	v_mov_b32_e32 v54, v47
	v_mov_b32_e32 v96, v55
	s_waitcnt vmcnt(22)
	v_lshlrev_b32_e32 v44, 16, v194
	s_waitcnt vmcnt(21)
	v_lshlrev_b32_e32 v45, 16, v195
	v_pk_mul_f32 v[52:53], v[46:47], v[44:45]
	v_rcp_f32_e32 v60, v55
	v_pk_mul_f32 v[84:85], v[54:55], v[164:165] neg_lo:[0,1] neg_hi:[0,1]
	global_load_ushort v102, v[162:163], off offset:128
	global_load_dword v87, v[160:161], off offset:512
	global_load_dword v86, v[100:101], off offset:512
	s_nop 0
	global_load_ushort v100, v[104:105], off offset:128
	global_load_ushort v101, v[98:99], off offset:128
	v_pk_mul_f32 v[4:5], v[56:57], v[4:5]
	v_rcp_f32_e32 v67, v47
	v_cvt_pk_bf16_f32 v104, v176, v177
	s_waitcnt vmcnt(25)
	v_lshlrev_b32_e32 v44, 16, v153
	s_waitcnt vmcnt(24)
; #define LAS __attribute__((address_space(3)))
; __device__ __forceinline__ float bf2f(bf16_t b) { return __uint_as_float((unsigned)b << 16); }
; __device__ __forceinline__ bf16_t cbf(float f) { return (bf16_t)(cpk(f, 0.f) & 0xffffu); }
; __device__ __forceinline__ void precompute(const char* rec, char* out, LAS char* wl, int lane) {
;     ...
;         LAS bf16_t* X = (LAS bf16_t*)wl;
; #pragma unroll
;         for (int t = 0; t < 16; ++t) {
;             const int idx = t * 64 + ((((lane >> 3) ^ ((t >> 1) & 7))) << 3) + (lane & 7);
;             const bf16_t bh = cbf(Bt[t]), ah = cbf(At[t]);
;             X[idx] = bh; X[1024 + idx] = cbf(Bt[t] - bf2f(bh)); X[2048 + idx] = ah; X[3072 + idx] = cbf(At[t] - bf2f(ah)); X[4096 + idx] = cbf(Kt[t]); X[5120 + idx] = cbf(Rt[t]);
;         }
	v_lshlrev_b32_e32 v45, 16, v154
	v_pk_mul_f32 v[54:55], v[96:97], v[44:45]
	v_cvt_pk_bf16_f32 v96, -v36, s0
	ds_write_b16 v21, v96 offset:4096
	v_lshlrev_b32_e32 v96, 16, v96
	v_sub_f32_e64 v36, -v36, v96
	v_cvt_pk_bf16_f32 v36, v36, s0
	ds_write_b16 v21, v36 offset:6144
	v_cvt_pk_bf16_f32 v36, v12, s0
	ds_write_b16 v21, v36 offset:10240
	v_cvt_pk_bf16_f32 v36, v142, s0
	ds_write_b16 v21, v36 offset:4224
	v_lshlrev_b32_e32 v36, 16, v36
	v_fma_f32 v2, v6, -v2, -v36
	v_cvt_pk_bf16_f32 v2, v2, s0
	ds_write_b16 v21, v2 offset:6272
	v_cvt_pk_bf16_f32 v2, v13, s0
	ds_write_b16 v21, v2 offset:10368
	v_cvt_pk_bf16_f32 v2, v72, s0
	ds_write_b16 v108, v2 offset:4352
	v_lshlrev_b32_e32 v2, 16, v2
	v_sub_f32_e32 v2, v72, v2
	v_cvt_pk_bf16_f32 v2, v2, s0
	ds_write_b16 v108, v2 offset:6400
	v_cvt_pk_bf16_f32 v2, v14, s0
	ds_write_b16 v108, v2 offset:10496
	v_cvt_pk_bf16_f32 v2, v73, s0
	ds_write_b16 v108, v2 offset:4480
	v_lshlrev_b32_e32 v2, 16, v2
	v_sub_f32_e32 v2, v73, v2
	v_cvt_pk_bf16_f32 v2, v2, s0
	ds_write_b16 v108, v2 offset:6528
	v_cvt_pk_bf16_f32 v2, v15, s0
	ds_write_b16 v108, v2 offset:10624
	v_cvt_pk_bf16_f32 v2, v74, s0
	ds_write_b16 v109, v2 offset:4608
	v_lshlrev_b32_e32 v2, 16, v2
	v_sub_f32_e32 v2, v74, v2
	v_cvt_pk_bf16_f32 v2, v2, s0
	ds_write_b16 v109, v2 offset:6656
	v_cvt_pk_bf16_f32 v2, v16, s0
	ds_write_b16 v109, v2 offset:10752
	v_cvt_pk_bf16_f32 v2, v75, s0
	ds_write_b16 v109, v2 offset:4736
	v_lshlrev_b32_e32 v2, 16, v2
	v_sub_f32_e32 v2, v75, v2
	v_cvt_pk_bf16_f32 v2, v2, s0
	ds_write_b16 v109, v2 offset:6784
	v_cvt_pk_bf16_f32 v2, v17, s0
	ds_write_b16 v109, v2 offset:10880
	v_cvt_pk_bf16_f32 v2, v76, s0
	ds_write_b16 v110, v2 offset:4864
	v_lshlrev_b32_e32 v2, 16, v2
	v_sub_f32_e32 v2, v76, v2
	v_cvt_pk_bf16_f32 v2, v2, s0
	ds_write_b16 v110, v2 offset:6912
	v_cvt_pk_bf16_f32 v2, v18, s0
	ds_write_b16 v110, v2 offset:11008
	v_cvt_pk_bf16_f32 v2, v77, s0
	ds_write_b16 v110, v2 offset:4992
	v_lshlrev_b32_e32 v2, 16, v2
	v_sub_f32_e32 v2, v77, v2
	v_cvt_pk_bf16_f32 v2, v2, s0
	ds_write_b16 v110, v2 offset:7040
	v_cvt_pk_bf16_f32 v2, v19, s0
	ds_write_b16 v110, v2 offset:11136
	v_cvt_pk_bf16_f32 v2, v78, s0
	ds_write_b16 v111, v2 offset:5120
	v_lshlrev_b32_e32 v2, 16, v2
	v_sub_f32_e32 v2, v78, v2
	v_cvt_pk_bf16_f32 v2, v2, s0
	ds_write_b16 v111, v2 offset:7168
	v_cvt_pk_bf16_f32 v2, v48, s0
	ds_write_b16 v111, v2 offset:11264
	v_cvt_pk_bf16_f32 v2, v79, s0
	ds_write_b16 v111, v2 offset:5248
	v_lshlrev_b32_e32 v2, 16, v2
	v_sub_f32_e32 v2, v79, v2
	v_cvt_pk_bf16_f32 v2, v2, s0
	ds_write_b16 v111, v2 offset:7296
	v_cvt_pk_bf16_f32 v2, v49, s0
	ds_write_b16 v111, v2 offset:11392
	v_cvt_pk_bf16_f32 v2, v80, s0
	ds_write_b16 v112, v2 offset:5376
	v_lshlrev_b32_e32 v2, 16, v2
	v_sub_f32_e32 v2, v80, v2
	v_cvt_pk_bf16_f32 v2, v2, s0
	ds_write_b16 v112, v2 offset:7424
	v_cvt_pk_bf16_f32 v2, v50, s0
	ds_write_b16 v112, v2 offset:11520
	v_cvt_pk_bf16_f32 v2, v81, s0
	ds_write_b16 v112, v2 offset:5504
	v_lshlrev_b32_e32 v2, 16, v2
	v_sub_f32_e32 v2, v81, v2
	s_waitcnt vmcnt(22)
	v_pk_mul_f32 v[94:95], v[68:69], v[94:95]
	v_cvt_pk_bf16_f32 v2, v2, s0
	v_cvt_pk_bf16_f32 v6, v94, s0
	ds_write_b16 v112, v2 offset:7552
	v_cvt_pk_bf16_f32 v2, v51, s0
	ds_write_b16 v108, v6 offset:256
	v_lshlrev_b32_e32 v6, 16, v6
	ds_write_b16 v112, v2 offset:11648
	v_cvt_pk_bf16_f32 v2, v82, s0
	v_sub_f32_e32 v6, v94, v6
	ds_write_b16 v113, v2 offset:5632
	v_lshlrev_b32_e32 v2, 16, v2
	v_cvt_pk_bf16_f32 v6, v6, s0
	v_sub_f32_e32 v2, v82, v2
	ds_write_b16 v108, v6 offset:2304
	v_cvt_pk_bf16_f32 v6, v95, s0
	v_cvt_pk_bf16_f32 v2, v2, s0
	ds_write_b16 v108, v6 offset:384
	v_lshlrev_b32_e32 v6, 16, v6
	ds_write_b16 v113, v2 offset:7680
	v_cvt_pk_bf16_f32 v2, v52, s0
	v_sub_f32_e32 v6, v95, v6
	ds_write_b16 v113, v2 offset:11776
	v_cvt_pk_bf16_f32 v2, v83, s0
	v_cvt_pk_bf16_f32 v6, v6, s0
	s_waitcnt vmcnt(17)
	v_pk_mul_f32 v[92:93], v[64:65], v[92:93]
	ds_write_b16 v113, v2 offset:5760
	v_lshlrev_b32_e32 v2, 16, v2
	ds_write_b16 v108, v6 offset:2432
	v_cvt_pk_bf16_f32 v6, v92, s0
	v_sub_f32_e32 v2, v83, v2
	ds_write_b16 v109, v6 offset:512
	v_lshlrev_b32_e32 v6, 16, v6
	v_cvt_pk_bf16_f32 v2, v2, s0
	v_sub_f32_e32 v6, v92, v6
	ds_write_b16 v113, v2 offset:7808
	v_cvt_pk_bf16_f32 v2, v53, s0
	v_cvt_pk_bf16_f32 v6, v6, s0
	ds_write_b16 v113, v2 offset:11904
	v_cvt_pk_bf16_f32 v2, v84, s0
	ds_write_b16 v109, v6 offset:2560
	v_cvt_pk_bf16_f32 v6, v93, s0
	ds_write_b16 v114, v2 offset:5888
	v_lshlrev_b32_e32 v2, 16, v2
	ds_write_b16 v109, v6 offset:640
	v_lshlrev_b32_e32 v6, 16, v6
	v_sub_f32_e32 v2, v84, v2
	v_sub_f32_e32 v6, v93, v6
	v_cvt_pk_bf16_f32 v2, v2, s0
	v_cvt_pk_bf16_f32 v6, v6, s0
	s_waitcnt vmcnt(15)
	v_pk_mul_f32 v[90:91], v[58:59], v[90:91]
	ds_write_b16 v114, v2 offset:7936
	v_cvt_pk_bf16_f32 v2, v54, s0
	ds_write_b16 v109, v6 offset:2688
	v_cvt_pk_bf16_f32 v6, v90, s0
	ds_write_b16 v114, v2 offset:12032
	v_cvt_pk_bf16_f32 v2, v85, s0
	ds_write_b16 v110, v6 offset:768
	v_lshlrev_b32_e32 v6, 16, v6
	ds_write_b16 v114, v2 offset:6016
	v_lshlrev_b32_e32 v2, 16, v2
	v_sub_f32_e32 v6, v90, v6
	v_sub_f32_e32 v2, v85, v2
	v_cvt_pk_bf16_f32 v6, v6, s0
	v_cvt_pk_bf16_f32 v2, v2, s0
	ds_write_b16 v110, v6 offset:2816
	v_cvt_pk_bf16_f32 v6, v91, s0
	ds_write_b16 v114, v2 offset:8064
	v_cvt_pk_bf16_f32 v2, v55, s0
	ds_write_b16 v110, v6 offset:896
	v_lshlrev_b32_e32 v6, 16, v6
	v_lshl_add_u64 v[44:45], s[38:39], 0, v[32:33]
	ds_write_b16 v114, v2 offset:12160
	v_cvt_pk_bf16_f32 v2, v4, s0
	v_sub_f32_e32 v6, v91, v6
	v_add_co_u32_e32 v46, vcc, s53, v44
	ds_write_b16 v21, v2
	v_lshlrev_b32_e32 v2, 16, v2
	v_cvt_pk_bf16_f32 v6, v6, s0
	s_waitcnt vmcnt(11)
; #define LAS __attribute__((address_space(3)))
; __device__ __forceinline__ float bf2f(bf16_t b) { return __uint_as_float((unsigned)b << 16); }
; __device__ __forceinline__ bf16_t cbf(float f) { return (bf16_t)(cpk(f, 0.f) & 0xffffu); }
; __device__ __forceinline__ u32x4 cpack8(const float* f) { u32x4 w; w.x = cpk(f[0], f[1]); w.y = cpk(f[2], f[3]); w.z = cpk(f[4], f[5]); w.w = cpk(f[6], f[7]); return w; }
; __device__ __forceinline__ s16x4 pack4(const f32x4& a) { u32x2 w; w.x = cpk(a.x, a.y); w.y = cpk(a.z, a.w); return __builtin_bit_cast(s16x4, w); }
; __device__ __forceinline__ void precompute(const char* rec, char* out, LAS char* wl, int lane) {
;     ...
;     for (int vt = 0; vt < 4; ++vt) *(s16x4*)(out + O_VB + vt * 512 + lane * 8) = pack4((f32x4){x.v[vt * 4 + 0], x.v[vt * 4 + 1], x.v[vt * 4 + 2], x.v[vt * 4 + 3]});
;     *(float*)(out + O_P + lane * 4) = P15;
;     {
;         LAS bf16_t* X = (LAS bf16_t*)wl;
; #pragma unroll
;         for (int t = 0; t < 16; ++t) {
;             const int idx = t * 64 + ((((lane >> 3) ^ ((t >> 1) & 7))) << 3) + (lane & 7);
;             const bf16_t bh = cbf(Bt[t]), ah = cbf(At[t]);
;             X[idx] = bh; X[1024 + idx] = cbf(Bt[t] - bf2f(bh)); X[2048 + idx] = ah; X[3072 + idx] = cbf(At[t] - bf2f(ah)); X[4096 + idx] = cbf(Kt[t]); X[5120 + idx] = cbf(Rt[t]);
;         }
;         float bc[16];
; #pragma unroll
;         for (int t = 0; t < 16; ++t) bc[t] = Bt[t] * P15;
;         LAS u32x4* at_t = (LAS u32x4*)(wl + 12288 + lane * 32); LAS u32x4* bc_t = (LAS u32x4*)(wl + 14336 + lane * 32);
;         at_t[0] = cpack8(At); at_t[1] = cpack8(At + 8); bc_t[0] = cpack8(bc); bc_t[1] = cpack8(bc + 8);
	v_pk_mul_f32 v[8:9], v[70:71], v[8:9]
	v_cvt_pk_bf16_f32 v105, v178, v179
	v_addc_co_u32_e32 v47, vcc, 0, v45, vcc
	v_sub_f32_e32 v2, v4, v2
	ds_write_b16 v110, v6 offset:2944
	v_cvt_pk_bf16_f32 v6, v8, s0
	v_lshl_add_u64 v[98:99], v[44:45], 0, s[42:43]
	global_store_dwordx2 v[46:47], v[104:105], off offset:512
	v_cvt_pk_bf16_f32 v104, v182, v183
	v_cvt_pk_bf16_f32 v105, v184, v151
	v_cvt_pk_bf16_f32 v2, v2, s0
	ds_write_b16 v111, v6 offset:1024
	v_lshlrev_b32_e32 v6, 16, v6
	v_lshlrev_b32_e32 v148, 16, v148
	v_lshlrev_b32_e32 v149, 16, v149
	v_lshlrev_b32_e32 v150, 16, v150
	global_store_dwordx2 v[98:99], v[104:105], off offset:512
	v_cvt_pk_bf16_f32 v104, v145, v185
	v_cvt_pk_bf16_f32 v105, v152, v146
	ds_write_b16 v21, v2 offset:2048
	v_cvt_pk_bf16_f32 v2, v5, s0
	v_sub_f32_e32 v6, v8, v6
	global_store_dwordx2 v[98:99], v[104:105], off offset:1024
	v_cvt_pk_bf16_f32 v104, v147, v148
	v_cvt_pk_bf16_f32 v105, v149, v150
	ds_write_b16 v21, v2 offset:128
	v_lshlrev_b32_e32 v2, 16, v2
	v_cvt_pk_bf16_f32 v6, v6, s0
	global_store_dwordx2 v[98:99], v[104:105], off offset:1536
	v_lshl_add_u64 v[98:99], s[38:39], 0, v[34:35]
	v_sub_f32_e32 v2, v5, v2
	ds_write_b16 v111, v6 offset:3072
	v_cvt_pk_bf16_f32 v6, v9, s0
	v_add_co_u32_e32 v98, vcc, s53, v98
	v_cvt_pk_bf16_f32 v2, v2, s0
	ds_write_b16 v111, v6 offset:1152
	v_lshlrev_b32_e32 v6, 16, v6
	v_addc_co_u32_e32 v99, vcc, 0, v99, vcc
	ds_write_b16 v21, v2 offset:2176
	v_mov_b32_e32 v2, v97
	v_sub_f32_e32 v6, v9, v6
	v_rcp_f32_e32 v61, v97
	global_store_dword v[98:99], v97, off offset:2560
	v_cvt_pk_bf16_f32 v6, v6, s0
	v_pk_mul_f32 v[96:97], v[8:9], v[2:3] op_sel_hi:[1,0]
	s_waitcnt vmcnt(13)
	v_pk_mul_f32 v[8:9], v[62:63], v[88:89]
	ds_write_b16 v111, v6 offset:3200
	v_cvt_pk_bf16_f32 v6, v8, s0
	ds_write_b16 v112, v6 offset:1280
	v_lshlrev_b32_e32 v6, 16, v6
	v_sub_f32_e32 v6, v8, v6
	v_cvt_pk_bf16_f32 v6, v6, s0
	ds_write_b16 v112, v6 offset:3328
	v_cvt_pk_bf16_f32 v6, v9, s0
	ds_write_b16 v112, v6 offset:1408
	v_lshlrev_b32_e32 v6, 16, v6
	v_sub_f32_e32 v6, v9, v6
	v_cvt_pk_bf16_f32 v6, v6, s0
	v_pk_mul_f32 v[88:89], v[8:9], v[2:3] op_sel_hi:[1,0]
	v_pk_mul_f32 v[8:9], v[66:67], v[10:11]
	ds_write_b16 v112, v6 offset:3456
	v_cvt_pk_bf16_f32 v6, v8, s0
	ds_write_b16 v113, v6 offset:1536
	v_lshlrev_b32_e32 v6, 16, v6
	v_sub_f32_e32 v6, v8, v6
	v_cvt_pk_bf16_f32 v6, v6, s0
	ds_write_b16 v113, v6 offset:3584
	v_cvt_pk_bf16_f32 v6, v9, s0
	ds_write_b16 v113, v6 offset:1664
	v_lshlrev_b32_e32 v6, 16, v6
	v_sub_f32_e32 v6, v9, v6
	v_cvt_pk_bf16_f32 v6, v6, s0
	v_pk_mul_f32 v[98:99], v[8:9], v[2:3] op_sel_hi:[1,0]
	s_waitcnt vmcnt(7)
	v_pk_mul_f32 v[8:9], v[60:61], v[86:87]
	ds_write_b16 v113, v6 offset:3712
	v_cvt_pk_bf16_f32 v6, v8, s0
	ds_write_b16 v114, v6 offset:1792
	v_lshlrev_b32_e32 v6, 16, v6
	v_sub_f32_e32 v6, v8, v6
	v_cvt_pk_bf16_f32 v6, v6, s0
	ds_write_b16 v114, v6 offset:3840
	v_cvt_pk_bf16_f32 v6, v9, s0
	ds_write_b16 v114, v6 offset:1920
	v_lshlrev_b32_e32 v6, 16, v6
	v_sub_f32_e32 v6, v9, v6
	v_pk_mul_f32 v[86:87], v[2:3], v[8:9] op_sel_hi:[0,1]
	v_cvt_pk_bf16_f32 v8, v141, v142
	v_cvt_pk_bf16_f32 v9, v72, v73
	v_cvt_pk_bf16_f32 v10, v74, v75
	v_cvt_pk_bf16_f32 v11, v76, v77
	v_pk_mul_f32 v[4:5], v[4:5], v[2:3] op_sel_hi:[1,0]
	ds_write_b128 v121, v[8:11] offset:12288
	v_cvt_pk_bf16_f32 v8, v78, v79
	v_cvt_pk_bf16_f32 v9, v80, v81
	v_cvt_pk_bf16_f32 v10, v82, v83
	v_cvt_pk_bf16_f32 v11, v84, v85
	ds_write_b128 v121, v[8:11] offset:12304
	v_cvt_pk_bf16_f32 v8, v4, v5
	v_lshlrev_b32_e32 v4, 16, v131
	v_lshlrev_b32_e32 v5, 16, v130
	v_pk_mul_f32 v[56:57], v[56:57], v[4:5]
	v_lshlrev_b32_e32 v5, 16, v133
	v_cvt_pk_bf16_f32 v4, v56, s0
	ds_write_b16 v21, v4 offset:8192
	v_cvt_pk_bf16_f32 v4, v57, s0
	ds_write_b16 v21, v4 offset:8320
	v_lshlrev_b32_e32 v4, 16, v132
	v_pk_mul_f32 v[68:69], v[68:69], v[4:5]
	v_lshlrev_b32_e32 v5, 16, v139
	v_cvt_pk_bf16_f32 v4, v68, s0
	ds_write_b16 v108, v4 offset:8448
	v_cvt_pk_bf16_f32 v4, v69, s0
	ds_write_b16 v108, v4 offset:8576
	v_lshlrev_b32_e32 v4, 16, v7
	v_pk_mul_f32 v[64:65], v[64:65], v[4:5]
	v_lshlrev_b32_e32 v5, 16, v136
	v_cvt_pk_bf16_f32 v4, v64, s0
	ds_write_b16 v109, v4 offset:8704
	v_cvt_pk_bf16_f32 v4, v65, s0
	ds_write_b16 v109, v4 offset:8832
	v_lshlrev_b32_e32 v4, 16, v135
	v_pk_mul_f32 v[58:59], v[58:59], v[4:5]
	v_lshlrev_b32_e32 v5, 16, v140
	v_cvt_pk_bf16_f32 v4, v58, s0
	ds_write_b16 v110, v4 offset:8960
	v_cvt_pk_bf16_f32 v4, v59, s0
	ds_write_b16 v110, v4 offset:9088
	v_lshlrev_b32_e32 v4, 16, v134
	v_pk_mul_f32 v[70:71], v[70:71], v[4:5]
	v_lshlrev_b32_e32 v5, 16, v138
	v_cvt_pk_bf16_f32 v4, v70, s0
	ds_write_b16 v111, v4 offset:9216
	v_cvt_pk_bf16_f32 v4, v71, s0
	ds_write_b16 v111, v4 offset:9344
	v_lshlrev_b32_e32 v4, 16, v137
	v_pk_mul_f32 v[62:63], v[62:63], v[4:5]
	s_waitcnt vmcnt(5)
	v_lshlrev_b32_e32 v5, 16, v101
	v_cvt_pk_bf16_f32 v4, v62, s0
	ds_write_b16 v112, v4 offset:9472
	v_cvt_pk_bf16_f32 v4, v63, s0
	ds_write_b16 v112, v4 offset:9600
	v_lshlrev_b32_e32 v4, 16, v129
	v_pk_mul_f32 v[66:67], v[66:67], v[4:5]
	v_lshlrev_b32_e32 v5, 16, v102
	v_cvt_pk_bf16_f32 v4, v66, s0
	ds_write_b16 v113, v4 offset:9728
	v_cvt_pk_bf16_f32 v4, v67, s0
	ds_write_b16 v113, v4 offset:9856
	v_lshlrev_b32_e32 v4, 16, v100
	v_pk_mul_f32 v[94:95], v[94:95], v[2:3] op_sel_hi:[1,0]
	v_pk_mul_f32 v[92:93], v[92:93], v[2:3] op_sel_hi:[1,0]
	v_pk_mul_f32 v[90:91], v[90:91], v[2:3] op_sel_hi:[1,0]
	v_pk_mul_f32 v[60:61], v[60:61], v[4:5]
	v_cvt_pk_bf16_f32 v9, v94, v95
	v_cvt_pk_bf16_f32 v10, v92, v93
	v_cvt_pk_bf16_f32 v11, v90, v91
	v_cvt_pk_bf16_f32 v4, v60, s0
	v_cvt_pk_bf16_f32 v6, v6, s0
	ds_write_b128 v121, v[8:11] offset:14336
	v_cvt_pk_bf16_f32 v8, v96, v97
	v_cvt_pk_bf16_f32 v9, v88, v89
	v_cvt_pk_bf16_f32 v10, v98, v99
	v_cvt_pk_bf16_f32 v11, v86, v87
	ds_write_b16 v114, v4 offset:9984
	v_cvt_pk_bf16_f32 v4, v61, s0
	ds_write_b16 v114, v6 offset:3968
	ds_write_b128 v121, v[8:11] offset:14352
	ds_write_b16 v114, v4 offset:10112
	s_waitcnt lgkmcnt(0)
; #define LAS __attribute__((address_space(3)))
; __device__ __forceinline__ bf16_t cbf(float f) { return (bf16_t)(cpk(f, 0.f) & 0xffffu); }
; __device__ __forceinline__ u32x4 cpack8(const float* f) { u32x4 w; w.x = cpk(f[0], f[1]); w.y = cpk(f[2], f[3]); w.z = cpk(f[4], f[5]); w.w = cpk(f[6], f[7]); return w; }
; __device__ __forceinline__ void precompute(const char* rec, char* out, LAS char* wl, int lane) {
;     ...
;     f32x4 Nc = zero4, Makc = zero4, Mrbc = zero4, Mrkc = zero4;
;     {
; #pragma unroll
;         for (int s2 = 0; s2 < 2; ++s2) {
;             const int off = fr * 128 + (((fq + 4 * s2) ^ ((fr >> 1) & 7)) << 4);
;             const bf16x8 bh = *(LAS const bf16x8*)(wl + off), bl = *(LAS const bf16x8*)(wl + 2048 + off), ah = *(LAS const bf16x8*)(wl + 4096 + off), al = *(LAS const bf16x8*)(wl + 6144 + off);
;             const bf16x8 kh = *(LAS const bf16x8*)(wl + 8192 + off), rh = *(LAS const bf16x8*)(wl + 10240 + off);
;             Nc = mm32(bh, ah, Nc); Nc = mm32(bh, al, Nc); Nc = mm32(bl, ah, Nc);
;             Makc = mm32(kh, ah, Makc); Mrbc = mm32(bh, rh, Mrbc); Mrkc = mm32(kh, rh, Mrkc);
;         }
; #pragma unroll
;         for (int j = 0; j < 4; ++j) { const int i = 4 * fq + j; if (!(i < fr)) { Nc[j] = 0.f; Makc[j] = 0.f; } if (!(i <= fr)) { Mrbc[j] = 0.f; Mrkc[j] = 0.f; } }
;     }
;     CHK_LW();
;     {
;         LAS float* NS = (LAS float*)wl; LAS bf16_t* MAK = (LAS bf16_t*)(wl + 1536);
; #pragma unroll
;         for (int j = 0; j < 4; ++j) { NS[(4 * fq + j) * 16 + fr] = Nc[j]; MAK[(4 * fq + j) * 16 + fr] = cbf(Makc[j]); }
;         CHK_LW();
;         float T[16];
; #pragma unroll
;         for (int i = 15; i >= 0; --i) {
;             float acc = 0.f;
; #pragma unroll
;             for (int q4 = (i + 1) / 4; q4 < 4; ++q4) { const f32x4 nv = *(LAS const f32x4*)(NS + i * 16 + q4 * 4);
; #pragma unroll
;                 for (int e = 0; e < 4; ++e) { const int jj = q4 * 4 + e; if (jj > i) acc += nv[e] * T[jj]; } }
;             T[i] = (i == fr) ? 1.f : ((i < fr) ? acc : 0.f);
;         }
;         LAS u32x4* tt = (LAS u32x4*)(wl + 1024 + fr * 32);
;         tt[0] = cpack8(T); tt[1] = cpack8(T + 8);
; __global__ void __launch_bounds__(NWAVES * 64, 2) mk_fwd(Args args) {
;     ...
; #pragma unroll 1
;                 for (int it = gw; it < NIT; it += ngw) chk::precompute(REC_OF(it), chkb + (size_t)it * chk::CHKB, wl, lane);
	ds_read_b128 v[4:7], v122
	ds_read_b128 v[8:11], v122 offset:4096
	ds_read_b128 v[72:75], v122 offset:2048
	ds_read_b128 v[76:79], v122 offset:6144
	s_waitcnt lgkmcnt(2)
	v_mfma_f32_16x16x32_bf16 v[80:83], v[4:7], v[8:11], 0
	ds_read_b128 v[84:87], v122 offset:8192
	ds_read_b128 v[88:91], v122 offset:10240
	s_or_b64 vcc, s[6:7], s[0:1]
	s_waitcnt lgkmcnt(2)
	v_mfma_f32_16x16x32_bf16 v[80:83], v[4:7], v[76:79], v[80:83]
	v_mov_b32_e32 v129, s48
	v_readlane_b32 s42, v255, 16
	v_mfma_f32_16x16x32_bf16 v[76:79], v[72:75], v[8:11], v[80:83]
	v_readlane_b32 s43, v255, 17
	v_cvt_pk_bf16_f32 v12, v12, v13
	s_waitcnt lgkmcnt(1)
	v_mfma_f32_16x16x32_bf16 v[80:83], v[84:87], v[8:11], 0
	v_cvt_pk_bf16_f32 v13, v14, v15
	v_cvt_pk_bf16_f32 v14, v16, v17
	s_waitcnt lgkmcnt(0)
	v_mfma_f32_16x16x32_bf16 v[92:95], v[4:7], v[88:91], 0
	v_cvt_pk_bf16_f32 v15, v18, v19
	v_pk_mul_f32 v[68:69], v[68:69], v[2:3] op_sel_hi:[1,0]
	v_mfma_f32_16x16x32_bf16 v[8:11], v[84:87], v[88:91], 0
	ds_read_b128 v[72:75], v123
	ds_read_b128 v[84:87], v123 offset:4096
	ds_read_b128 v[88:91], v123 offset:2048
	ds_read_b128 v[4:7], v123 offset:6144
	ds_read_b128 v[96:99], v123 offset:8192
	ds_read_b128 v[100:103], v123 offset:10240
	s_waitcnt lgkmcnt(4)
	v_mfma_f32_16x16x32_bf16 v[76:79], v[72:75], v[84:87], v[76:79]
	v_pk_mul_f32 v[64:65], v[64:65], v[2:3] op_sel_hi:[1,0]
	v_pk_mul_f32 v[70:71], v[70:71], v[2:3] op_sel_hi:[1,0]
	s_waitcnt lgkmcnt(2)
	v_mfma_f32_16x16x32_bf16 v[76:79], v[72:75], v[4:7], v[76:79]
	v_pk_mul_f32 v[62:63], v[62:63], v[2:3] op_sel_hi:[1,0]
	v_pk_mul_f32 v[66:67], v[66:67], v[2:3] op_sel_hi:[1,0]
	v_mfma_f32_16x16x32_bf16 v[76:79], v[88:91], v[84:87], v[76:79]
	s_add_u32 s40, s40, s19
	s_addc_u32 s41, s41, s49
	s_and_b32 s98, s40, 7
	s_bfe_u32 s99, s40, 0x80003
	s_lshl_b32 s99, s99, 1
	s_add_i32 s99, s99, s98
	s_add_i32 s99, s99, 0x4000
	s_cmp_lt_u32 s98, 2
	s_cselect_b32 s99, s99, 0x7fffff
	s_cmp_lt_u32 s40, 0x4800
	s_cselect_b32 s99, s99, s40
	s_cmp_lt_u32 s40, 0x4000
	s_cselect_b32 s40, s40, s99
	s_waitcnt lgkmcnt(1)
	v_mfma_f32_16x16x32_bf16 v[80:83], v[96:99], v[84:87], v[80:83]
	s_nop 3
	v_cndmask_b32_e64 v78, 0, v78, s[4:5]
	v_cndmask_b32_e64 v77, 0, v77, s[6:7]
	s_waitcnt lgkmcnt(0)
	v_mfma_f32_16x16x32_bf16 v[4:7], v[72:75], v[100:103], v[92:95]
	v_cndmask_b32_e64 v36, 0, v83, s[36:37]
	v_cndmask_b32_e64 v72, 0, v82, s[4:5]
	v_cndmask_b32_e64 v73, 0, v81, s[6:7]
	v_cndmask_b32_e32 v74, 0, v80, vcc
	v_mfma_f32_16x16x32_bf16 v[8:11], v[96:99], v[100:103], v[8:11]
	v_cvt_pk_bf16_f32 v74, v74, s0
	v_cvt_pk_bf16_f32 v73, v73, s0
	v_cvt_pk_bf16_f32 v72, v72, s0
	v_cvt_pk_bf16_f32 v36, v36, s0
	v_cndmask_b32_e64 v75, 0, v79, s[36:37]
	v_cndmask_b32_e32 v76, 0, v76, vcc
	s_waitcnt lgkmcnt(0)
	ds_write_b16 v128, v74 offset:1536
	ds_write2_b32 v115, v76, v77 offset1:16
	ds_write_b16 v128, v73 offset:1568
	ds_write_b16 v128, v72 offset:1600
	ds_write2_b32 v115, v78, v75 offset0:32 offset1:48
	ds_write_b16 v128, v36 offset:1632
	s_waitcnt lgkmcnt(0)
	ds_read_b128 v[72:75], v129 offset:944
	ds_read_b128 v[76:79], v129 offset:816
	ds_read_b128 v[80:83], v129 offset:752
	ds_read_b128 v[84:87], v129 offset:672
	ds_read_b128 v[88:91], v129 offset:688
	ds_read_b128 v[92:95], v129 offset:624
	ds_read_b128 v[96:99], v129 offset:560
	ds_read_b128 v[100:103], v129 offset:544
	ds_read_b128 v[104:107], v129 offset:496
	ds_read_b128 v[130:133], v129 offset:400
	ds_read_b128 v[134:137], v129 offset:416
	ds_read_b128 v[138:141], v129 offset:480
	ds_read_b128 v[142:145], v129 offset:432
	ds_read_b128 v[146:149], v129 offset:352
	ds_read_b128 v[150:153], v129 offset:368
	ds_read_b128 v[154:157], v129 offset:288
	ds_read_b128 v[158:161], v129 offset:304
	ds_read_b128 v[172:175], v129 offset:208
	ds_read_b128 v[176:179], v129 offset:224
	ds_read_b128 v[180:183], v129 offset:272
	ds_read_b128 v[184:187], v129 offset:240
	ds_read_b128 v[206:209], v129 offset:128
	ds_read_b128 v[210:213], v129 offset:144
	ds_read_b128 v[214:217], v129 offset:160
	ds_read_b128 v[218:221], v129 offset:176
	ds_read_b128 v[222:225], v129 offset:64
	ds_read_b128 v[226:229], v129 offset:80
	ds_read_b128 v[230:233], v129 offset:96
	ds_read_b128 v[234:237], v129 offset:112
	ds_read_b128 v[238:241], v129
	ds_read_b128 v[242:245], v129 offset:16
	s_waitcnt lgkmcnt(14)
	ds_read_b64 v[72:73], v129 offset:888
	ds_read_b128 v[246:249], v129 offset:32
	ds_read_b128 v[162:165], v129 offset:48
	v_fma_f32 v36, v37, v75, 0
	v_cndmask_b32_e64 v36, 0, v36, s[92:93]
	v_cndmask_b32_e64 v36, v36, 1.0, s[90:91]
	s_waitcnt lgkmcnt(2)
	v_pk_mul_f32 v[72:73], v[36:37], v[72:73]
	v_pk_mul_f32 v[84:85], v[36:37], v[94:95]
	v_add_f32_e32 v72, 0, v72
	v_add_f32_e32 v72, v73, v72
	v_cndmask_b32_e64 v74, 0, v72, s[88:89]
	v_pk_mul_f32 v[72:73], v[36:37], v[78:79]
	v_pk_mul_f32 v[78:79], v[36:37], v[82:83]
	v_pk_mul_f32 v[82:83], v[36:37], v[90:91]
	v_pk_mul_f32 v[90:91], v[36:37], v[98:99]
	v_cndmask_b32_e64 v99, v74, 1.0, s[86:87]
	v_fma_f32 v74, v77, v99, 0
	v_add_f32_e32 v72, v72, v74
	v_add_f32_e32 v86, v73, v72
	v_cndmask_b32_e64 v86, 0, v86, s[84:85]
	v_cndmask_b32_e64 v98, v86, 1.0, s[82:83]
	v_pk_mul_f32 v[80:81], v[80:81], v[98:99]
	v_pk_mul_f32 v[88:89], v[88:89], v[98:99]
	v_add_f32_e32 v80, 0, v80
	v_add_f32_e32 v86, v81, v80
	v_add_f32_e32 v78, v78, v86
	v_add_f32_e32 v86, v79, v78
	v_cndmask_b32_e64 v86, 0, v86, s[80:81]
	v_pk_mul_f32 v[78:79], v[36:37], v[186:187]
	v_cndmask_b32_e64 v187, v86, 1.0, s[78:79]
	v_fma_f32 v86, v87, v187, 0
	v_add_f32_e32 v86, v88, v86
	ds_read2_b64 v[72:75], v129 offset0:43 offset1:77
	v_add_f32_e32 v86, v89, v86
	v_add_f32_e32 v82, v82, v86
	v_add_f32_e32 v82, v83, v82
	v_cndmask_b32_e64 v82, 0, v82, s[76:77]
	v_cndmask_b32_e64 v186, v82, 1.0, s[74:75]
	s_waitcnt lgkmcnt(0)
; #define LAS __attribute__((address_space(3)))
; __device__ __forceinline__ u32x4 cpack8(const float* f) { u32x4 w; w.x = cpk(f[0], f[1]); w.y = cpk(f[2], f[3]); w.z = cpk(f[4], f[5]); w.w = cpk(f[6], f[7]); return w; }
; __device__ __forceinline__ void precompute(const char* rec, char* out, LAS char* wl, int lane) {
;     ...
;         float T[16];
; #pragma unroll
;         for (int i = 15; i >= 0; --i) {
;             float acc = 0.f;
; #pragma unroll
;             for (int q4 = (i + 1) / 4; q4 < 4; ++q4) { const f32x4 nv = *(LAS const f32x4*)(NS + i * 16 + q4 * 4);
; #pragma unroll
;                 for (int e = 0; e < 4; ++e) { const int jj = q4 * 4 + e; if (jj > i) acc += nv[e] * T[jj]; } }
;             T[i] = (i == fr) ? 1.f : ((i < fr) ? acc : 0.f);
;         }
;         LAS u32x4* tt = (LAS u32x4*)(wl + 1024 + fr * 32);
;         tt[0] = cpack8(T); tt[1] = cpack8(T + 8);
	v_pk_mul_f32 v[74:75], v[74:75], v[186:187]
	v_pk_mul_f32 v[92:93], v[92:93], v[98:99]
	v_add_f32_e32 v74, 0, v74
	v_add_f32_e32 v74, v75, v74
	v_add_f32_e32 v74, v92, v74
	v_add_f32_e32 v74, v93, v74
	v_add_f32_e32 v74, v84, v74
	v_add_f32_e32 v74, v85, v74
	v_cndmask_b32_e64 v100, 0, v74, s[72:73]
	v_pk_mul_f32 v[82:83], v[140:141], v[186:187]
	v_cndmask_b32_e64 v141, v100, 1.0, s[70:71]
	v_pk_mul_f32 v[74:75], v[102:103], v[186:187]
	v_fma_f32 v100, v101, v141, 0
	v_add_f32_e32 v74, v74, v100
	v_pk_mul_f32 v[96:97], v[96:97], v[98:99]
	v_add_f32_e32 v74, v75, v74
	v_add_f32_e32 v74, v96, v74
	v_add_f32_e32 v74, v97, v74
	v_add_f32_e32 v74, v90, v74
	v_add_f32_e32 v74, v91, v74
	v_cndmask_b32_e64 v74, 0, v74, s[68:69]
	v_cndmask_b32_e64 v140, v74, 1.0, s[66:67]
	v_pk_mul_f32 v[74:75], v[138:139], v[140:141]
	v_pk_mul_f32 v[104:105], v[98:99], v[104:105]
	v_add_f32_e32 v74, 0, v74
	v_add_f32_e32 v74, v75, v74
	v_add_f32_e32 v74, v82, v74
	v_add_f32_e32 v74, v83, v74
	v_add_f32_e32 v74, v104, v74
	v_pk_mul_f32 v[94:95], v[36:37], v[106:107]
	v_add_f32_e32 v74, v105, v74
	v_add_f32_e32 v74, v94, v74
	v_add_f32_e32 v74, v95, v74
	v_cndmask_b32_e64 v104, 0, v74, s[64:65]
	v_cndmask_b32_e64 v105, v104, 1.0, s[62:63]
	v_pk_mul_f32 v[74:75], v[134:135], v[140:141]
	v_fma_f32 v104, v133, v105, 0
	v_add_f32_e32 v74, v74, v104
	v_pk_mul_f32 v[84:85], v[136:137], v[186:187]
	v_add_f32_e32 v74, v75, v74
	v_add_f32_e32 v74, v84, v74
	v_pk_mul_f32 v[142:143], v[98:99], v[142:143]
	v_add_f32_e32 v74, v85, v74
	v_add_f32_e32 v74, v142, v74
	v_pk_mul_f32 v[76:77], v[36:37], v[144:145]
	v_add_f32_e32 v74, v143, v74
	v_add_f32_e32 v74, v76, v74
	v_add_f32_e32 v74, v77, v74
	v_cndmask_b32_e64 v74, 0, v74, s[60:61]
	v_cndmask_b32_e64 v104, v74, 1.0, s[58:59]
	v_pk_mul_f32 v[72:73], v[72:73], v[104:105]
	v_pk_mul_f32 v[82:83], v[146:147], v[140:141]
	v_add_f32_e32 v72, 0, v72
	v_add_f32_e32 v72, v73, v72
	v_add_f32_e32 v72, v82, v72
	v_pk_mul_f32 v[86:87], v[148:149], v[186:187]
	v_add_f32_e32 v72, v83, v72
	v_add_f32_e32 v72, v86, v72
	v_pk_mul_f32 v[150:151], v[98:99], v[150:151]
	v_add_f32_e32 v72, v87, v72
	v_add_f32_e32 v72, v150, v72
	v_pk_mul_f32 v[106:107], v[36:37], v[152:153]
	v_add_f32_e32 v72, v151, v72
	v_add_f32_e32 v72, v106, v72
	v_add_f32_e32 v72, v107, v72
	v_cndmask_b32_e64 v72, 0, v72, s[56:57]
	v_cndmask_b32_e64 v74, v72, 1.0, s[54:55]
	v_fma_f32 v75, v181, v74, 0
	v_pk_mul_f32 v[72:73], v[182:183], v[104:105]
	v_pk_mul_f32 v[90:91], v[154:155], v[140:141]
	v_add_f32_e32 v72, v72, v75
	v_add_f32_e32 v72, v73, v72
	v_add_f32_e32 v72, v90, v72
	v_pk_mul_f32 v[88:89], v[156:157], v[186:187]
	v_add_f32_e32 v72, v91, v72
	v_add_f32_e32 v72, v88, v72
	v_pk_mul_f32 v[152:153], v[98:99], v[158:159]
	v_add_f32_e32 v72, v89, v72
	v_add_f32_e32 v72, v152, v72
	v_pk_mul_f32 v[80:81], v[36:37], v[160:161]
	v_add_f32_e32 v72, v153, v72
	v_add_f32_e32 v72, v80, v72
	v_add_f32_e32 v72, v81, v72
	v_cndmask_b32_e64 v72, 0, v72, s[42:43]
	v_readlane_b32 s42, v255, 14
	v_readlane_b32 s43, v255, 15
	v_pk_mul_f32 v[94:95], v[176:177], v[140:141]
	v_pk_mul_f32 v[92:93], v[178:179], v[186:187]
	v_cndmask_b32_e64 v75, v72, 1.0, s[42:43]
	v_fma_f32 v76, v172, v75, 0
	v_fmac_f32_e32 v76, v173, v74
	v_pk_mul_f32 v[72:73], v[174:175], v[104:105]
	v_pk_mul_f32 v[158:159], v[98:99], v[184:185]
	v_add_f32_e32 v72, v72, v76
	v_add_f32_e32 v72, v73, v72
	v_add_f32_e32 v72, v94, v72
	v_add_f32_e32 v72, v95, v72
	v_add_f32_e32 v72, v92, v72
	v_add_f32_e32 v72, v93, v72
	v_add_f32_e32 v72, v158, v72
	v_add_f32_e32 v72, v159, v72
	v_add_f32_e32 v72, v78, v72
	v_readlane_b32 s42, v255, 12
	v_add_f32_e32 v72, v79, v72
	v_readlane_b32 s43, v255, 13
	v_pk_mul_f32 v[96:97], v[214:215], v[140:141]
	v_pk_mul_f32 v[102:103], v[186:187], v[216:217]
	v_cndmask_b32_e64 v72, 0, v72, s[42:43]
	v_readlane_b32 s42, v255, 10
	v_readlane_b32 s43, v255, 11
	v_pk_mul_f32 v[160:161], v[98:99], v[218:219]
	v_pk_mul_f32 v[130:131], v[36:37], v[220:221]
	v_cndmask_b32_e64 v76, v72, 1.0, s[42:43]
	v_fma_f32 v77, v209, v76, 0
	v_fmac_f32_e32 v77, v210, v75
	v_fmac_f32_e32 v77, v211, v74
	v_pk_mul_f32 v[72:73], v[212:213], v[104:105]
	v_readlane_b32 s42, v255, 8
	v_add_f32_e32 v72, v72, v77
	v_add_f32_e32 v72, v73, v72
	v_add_f32_e32 v72, v96, v72
	v_add_f32_e32 v72, v97, v72
	v_add_f32_e32 v72, v102, v72
	v_add_f32_e32 v72, v103, v72
	v_add_f32_e32 v72, v160, v72
	v_add_f32_e32 v72, v161, v72
	v_add_f32_e32 v72, v130, v72
	v_add_f32_e32 v72, v131, v72
	v_readlane_b32 s43, v255, 9
	v_pk_mul_f32 v[100:101], v[230:231], v[140:141]
	v_pk_mul_f32 v[136:137], v[186:187], v[232:233]
	v_cndmask_b32_e64 v72, 0, v72, s[42:43]
	v_readlane_b32 s42, v255, 6
	v_readlane_b32 s43, v255, 7
	v_pk_mul_f32 v[184:185], v[98:99], v[234:235]
	v_pk_mul_f32 v[144:145], v[36:37], v[236:237]
	v_cndmask_b32_e64 v77, v72, 1.0, s[42:43]
	v_fma_f32 v78, v224, v77, 0
	v_fmac_f32_e32 v78, v225, v76
	v_fmac_f32_e32 v78, v226, v75
	v_fmac_f32_e32 v78, v227, v74
	v_pk_mul_f32 v[72:73], v[228:229], v[104:105]
	v_readlane_b32 s42, v255, 4
	v_add_f32_e32 v72, v72, v78
	v_add_f32_e32 v72, v73, v72
	v_add_f32_e32 v72, v100, v72
	v_add_f32_e32 v72, v101, v72
	v_add_f32_e32 v72, v136, v72
	v_add_f32_e32 v72, v137, v72
	v_add_f32_e32 v72, v184, v72
	v_add_f32_e32 v72, v185, v72
	v_add_f32_e32 v72, v144, v72
	v_add_f32_e32 v72, v145, v72
	v_readlane_b32 s43, v255, 5
	v_pk_mul_f32 v[92:93], v[56:57], v[2:3] op_sel_hi:[1,0]
	v_pk_mul_f32 v[94:95], v[58:59], v[2:3] op_sel_hi:[1,0]
	v_cndmask_b32_e64 v72, 0, v72, s[42:43]
	v_readlane_b32 s42, v255, 0
	v_readlane_b32 s43, v255, 1
	v_cndmask_b32_e64 v9, 0, v9, s[0:1]
	v_cndmask_b32_e64 v10, v10, 0, s[8:9]
	v_cndmask_b32_e64 v78, v72, 1.0, s[42:43]
	v_fma_f32 v79, v239, v78, 0
	v_fmac_f32_e32 v79, v240, v77
	v_fmac_f32_e32 v79, v241, v76
	v_fmac_f32_e32 v79, v242, v75
	v_fmac_f32_e32 v79, v243, v74
	v_pk_mul_f32 v[72:73], v[244:245], v[104:105]
	v_cvt_pk_bf16_f32 v74, v75, v74
	v_add_f32_e32 v72, v72, v79
	v_add_f32_e32 v79, v73, v72
	v_pk_mul_f32 v[72:73], v[246:247], v[140:141]
	v_cvt_pk_bf16_f32 v75, v104, v105
	v_add_f32_e32 v72, v72, v79
	v_add_f32_e32 v79, v73, v72
	v_pk_mul_f32 v[72:73], v[186:187], v[248:249]
	v_cndmask_b32_e64 v11, v11, 0, s[96:97]
	v_add_f32_e32 v72, v72, v79
	v_add_f32_e32 v79, v73, v72
	v_pk_mul_f32 v[72:73], v[98:99], v[162:163]
	s_add_u32 s46, s46, s50
	v_add_f32_e32 v72, v72, v79
	v_add_f32_e32 v79, v73, v72
	v_pk_mul_f32 v[72:73], v[36:37], v[164:165]
	s_addc_u32 s47, s47, s10
	v_add_f32_e32 v72, v72, v79
	v_add_f32_e32 v72, v73, v72
	v_cndmask_b32_e64 v72, v72, 1.0, s[2:3]
	v_cvt_pk_bf16_f32 v72, v72, v78
	v_cvt_pk_bf16_f32 v73, v77, v76
	ds_write_b128 v116, v[72:75] offset:1024
	v_cvt_pk_bf16_f32 v72, v140, v141
	v_cvt_pk_bf16_f32 v73, v186, v187
	v_cvt_pk_bf16_f32 v74, v98, v99
	v_cvt_pk_bf16_f32 v75, v36, v37
	ds_write_b128 v116, v[72:75] offset:1040
	s_waitcnt lgkmcnt(0)
; #define LAS __attribute__((address_space(3)))
; __device__ __forceinline__ u32x4 pack8(const float* f) { u32x4 w; w.x = cvtpk(f[0], f[1]); w.y = cvtpk(f[2], f[3]); w.z = cvtpk(f[4], f[5]); w.w = cvtpk(f[6], f[7]); return w; }
; __device__ __forceinline__ bf16_t cbf(float f) { return (bf16_t)(cpk(f, 0.f) & 0xffffu); }
; __device__ __forceinline__ u32x4 cpack8(const float* f) { u32x4 w; w.x = cpk(f[0], f[1]); w.y = cpk(f[2], f[3]); w.z = cpk(f[4], f[5]); w.w = cpk(f[6], f[7]); return w; }
; __device__ __forceinline__ s16x4 pack4(const f32x4& a) { u32x2 w; w.x = cpk(a.x, a.y); w.y = cpk(a.z, a.w); return __builtin_bit_cast(s16x4, w); }
; __device__ __forceinline__ void precompute(const char* rec, char* out, LAS char* wl, int lane) {
;     ...
;     const s16x4 TTf = CHK_A16(1024, 0);
;     {
;         LAS bf16_t* AH = (LAS bf16_t*)(wl + 2560); LAS bf16_t* MAKP = (LAS bf16_t*)(wl + 2048);
;         f32x4 ahc[4];
; #pragma unroll
;         for (int mk = 0; mk < 4; ++mk) ahc[mk] = mm16(CHK_A16(12288, 16 * mk), TTf, zero4);
;         const f32x4 makp = mm16(CHK_A16(1536, 0), TTf, zero4);
; #pragma unroll
;         for (int mk = 0; mk < 4; ++mk)
; #pragma unroll
;             for (int j = 0; j < 4; ++j) AH[(16 * mk + 4 * fq + j) * 16 + fr] = cbf(ahc[mk][j]);
; #pragma unroll
;         for (int j = 0; j < 4; ++j) MAKP[(4 * fq + j) * 16 + fr] = cbf(makp[j]);
;         float kc[16];
; #pragma unroll
;         for (int t = 0; t < 16; ++t) kc[t] = Kt[t] * P15;
;         LAS u32x4* rt_t = (LAS u32x4*)(wl + 4608 + lane * 32); LAS u32x4* kc_t = (LAS u32x4*)(wl + 6656 + lane * 32);
;         rt_t[0] = cpack8(Rt); rt_t[1] = cpack8(Rt + 8); kc_t[0] = cpack8(kc); kc_t[1] = cpack8(kc + 8);
;     }
;     CHK_LW();
;     const s16x4 Mrb_b = pack4(Mrbc);
;     s16x4 Ident;
; #pragma unroll
;     for (int e = 0; e < 4; ++e) Ident[e] = (4 * fq + e == fr) ? (short)0x3F80 : (short)0;
;     {
;         f32x4 rh[4];
; #pragma unroll
;         for (int mk = 0; mk < 4; ++mk) { f32x4 d = mm16(CHK_A16(2560, 16 * mk), Mrb_b, zero4); rh[mk] = mm16(CHK_A16(4608, 16 * mk), Ident, d); }
;         *(bf16x8*)(out + O_RA + lane * 16) = pack8(rh[0], rh[1]);
;         *(bf16x8*)(out + O_RA + 1024 + lane * 16) = pack8(rh[2], rh[3]);
;     }
;     { const f32x4 mo = mm16(CHK_A16(2048, 0), Mrb_b, Mrkc); *(s16x4*)(out + O_MA + lane * 8) = pack4(mo); }
	v_add_u32_e32 v36, v116, v117
	ds_read2st64_b64 v[72:75], v36 offset0:2 offset1:24
	s_waitcnt lgkmcnt(0)
	v_mfma_f32_16x16x16_bf16 v[76:79], v[74:75], v[72:73], 0
	ds_read_b64 v[74:75], v36 offset:12800
	s_cmpk_gt_i32 s40, 0x41ff
	s_waitcnt lgkmcnt(0)
	v_mfma_f32_16x16x16_bf16 v[80:83], v[74:75], v[72:73], 0
	ds_read_b64 v[74:75], v36 offset:13312
	s_waitcnt lgkmcnt(0)
	v_mfma_f32_16x16x16_bf16 v[84:87], v[74:75], v[72:73], 0
	ds_read_b64 v[74:75], v36 offset:13824
	s_waitcnt lgkmcnt(0)
	v_mfma_f32_16x16x16_bf16 v[88:91], v[74:75], v[72:73], 0
	ds_read_b64 v[74:75], v36 offset:1536
	s_waitcnt lgkmcnt(0)
	v_mfma_f32_16x16x16_bf16 v[56:59], v[74:75], v[72:73], 0
	v_cvt_pk_bf16_f32 v72, v76, s0
	v_add_u32_e32 v73, v118, v119
	ds_write_b16 v73, v72 offset:2560
	v_cvt_pk_bf16_f32 v72, v77, s0
	ds_write_b16 v124, v72 offset:2560
	v_cvt_pk_bf16_f32 v72, v78, s0
	ds_write_b16 v125, v72 offset:2560
	v_cvt_pk_bf16_f32 v72, v79, s0
	ds_write_b16 v126, v72 offset:2560
	v_cvt_pk_bf16_f32 v72, v80, s0
	ds_write_b16 v73, v72 offset:3072
	v_cvt_pk_bf16_f32 v72, v81, s0
	ds_write_b16 v73, v72 offset:3104
	v_cvt_pk_bf16_f32 v72, v82, s0
	ds_write_b16 v73, v72 offset:3136
	v_cvt_pk_bf16_f32 v72, v83, s0
	ds_write_b16 v73, v72 offset:3168
	v_cvt_pk_bf16_f32 v72, v84, s0
	ds_write_b16 v73, v72 offset:3584
	v_cvt_pk_bf16_f32 v72, v85, s0
	ds_write_b16 v73, v72 offset:3616
	v_cvt_pk_bf16_f32 v72, v86, s0
	ds_write_b16 v73, v72 offset:3648
	v_cvt_pk_bf16_f32 v72, v87, s0
	ds_write_b16 v73, v72 offset:3680
	v_cvt_pk_bf16_f32 v72, v88, s0
	ds_write_b16 v73, v72 offset:4096
	v_cvt_pk_bf16_f32 v72, v89, s0
	ds_write_b16 v73, v72 offset:4128
	v_cvt_pk_bf16_f32 v72, v90, s0
	ds_write_b16 v73, v72 offset:4160
	v_cvt_pk_bf16_f32 v72, v91, s0
	v_cvt_pk_bf16_f32 v56, v56, s0
	ds_write_b16 v73, v72 offset:4192
	ds_write_b16 v120, v56 offset:2048
	v_cvt_pk_bf16_f32 v56, v57, s0
	ds_write_b16 v120, v56 offset:2080
	v_cvt_pk_bf16_f32 v56, v58, s0
	ds_write_b16 v120, v56 offset:2112
	v_cvt_pk_bf16_f32 v56, v59, s0
	ds_write_b128 v121, v[12:15] offset:4608
	v_cvt_pk_bf16_f32 v12, v48, v49
	v_cvt_pk_bf16_f32 v13, v50, v51
	v_cvt_pk_bf16_f32 v14, v52, v53
	v_cvt_pk_bf16_f32 v15, v54, v55
	ds_write_b16 v120, v56 offset:2144
	v_pk_mul_f32 v[56:57], v[2:3], v[60:61] op_sel_hi:[0,1]
	ds_write_b128 v121, v[12:15] offset:4624
	v_cvt_pk_bf16_f32 v12, v92, v93
	v_cvt_pk_bf16_f32 v13, v68, v69
	v_cvt_pk_bf16_f32 v14, v64, v65
	v_cvt_pk_bf16_f32 v15, v94, v95
	ds_write_b128 v121, v[12:15] offset:6656
	v_cvt_pk_bf16_f32 v12, v70, v71
	v_cvt_pk_bf16_f32 v13, v62, v63
	v_cvt_pk_bf16_f32 v14, v66, v67
	v_cvt_pk_bf16_f32 v15, v56, v57
	ds_write_b128 v121, v[12:15] offset:6672
	s_waitcnt lgkmcnt(0)
	ds_read_b64 v[12:13], v127 offset:2560
	v_mov_b32_e32 v2, s11
	v_cndmask_b32_e64 v2, v4, v2, s[94:95]
	v_cndmask_b32_e64 v2, v2, v4, s[0:1]
	v_cndmask_b32_e64 v4, 0, v5, s[0:1]
	v_cndmask_b32_e64 v5, v6, 0, s[8:9]
	v_cndmask_b32_e64 v6, v7, 0, s[96:97]
	v_cvt_pk_bf16_f32 v50, v2, v4
	v_cvt_pk_bf16_f32 v51, v5, v6
	v_mov_b32_e32 v2, s11
	v_cndmask_b32_e64 v2, v8, v2, s[94:95]
	s_waitcnt lgkmcnt(0)
	v_mfma_f32_16x16x16_bf16 v[4:7], v[12:13], v[50:51], 0
	ds_read_b64 v[12:13], v127 offset:4608
	v_cndmask_b32_e64 v8, v2, v8, s[0:1]
	s_waitcnt lgkmcnt(0)
	v_mfma_f32_16x16x16_bf16 v[16:19], v[12:13], v[40:41], v[4:7]
	ds_read_b64 v[12:13], v127 offset:3072
	s_nop 6
	v_cvt_pk_bf16_f32 v16, v16, v17
	s_waitcnt lgkmcnt(0)
	v_mfma_f32_16x16x16_bf16 v[4:7], v[12:13], v[50:51], 0
	ds_read_b64 v[12:13], v127 offset:5120
	v_cvt_pk_bf16_f32 v17, v18, v19
	s_waitcnt lgkmcnt(0)
	v_mfma_f32_16x16x16_bf16 v[52:55], v[12:13], v[40:41], v[4:7]
	ds_read_b64 v[12:13], v127 offset:3584
	s_nop 6
	v_cvt_pk_bf16_f32 v18, v52, v53
	s_waitcnt lgkmcnt(0)
	v_mfma_f32_16x16x16_bf16 v[4:7], v[12:13], v[50:51], 0
	ds_read_b64 v[12:13], v127 offset:5632
	v_cvt_pk_bf16_f32 v19, v54, v55
	s_waitcnt lgkmcnt(0)
	v_mfma_f32_16x16x16_bf16 v[4:7], v[12:13], v[40:41], v[4:7]
	ds_read_b64 v[48:49], v127 offset:4096
	s_nop 6
	v_cvt_pk_bf16_f32 v4, v4, v5
	s_waitcnt lgkmcnt(0)
	v_mfma_f32_16x16x16_bf16 v[12:15], v[48:49], v[50:51], 0
	ds_read_b64 v[48:49], v127 offset:6144
	v_cvt_pk_bf16_f32 v5, v6, v7
	s_waitcnt lgkmcnt(0)
	v_mfma_f32_16x16x16_bf16 v[12:15], v[48:49], v[40:41], v[12:15]
	ds_read_b64 v[52:53], v36 offset:2048
	v_lshl_add_u64 v[48:49], s[38:39], 0, v[42:43]
	v_add_co_u32_e32 v54, vcc, s52, v48
	s_nop 4
	v_cvt_pk_bf16_f32 v6, v12, v13
	v_addc_co_u32_e32 v55, vcc, 0, v49, vcc
	v_cvt_pk_bf16_f32 v7, v14, v15
	global_store_dwordx4 v[54:55], v[4:7], off offset:1024
	global_store_dwordx4 v[54:55], v[16:19], off
	s_mov_b64 s[38:39], 0x2800
	s_waitcnt lgkmcnt(0)
	v_mfma_f32_16x16x16_bf16 v[4:7], v[52:53], v[50:51], v[8:11]
	s_nop 2
	ds_read_b64 v[8:9], v36 offset:2560
	ds_read_b64 v[50:51], v127 offset:14336
	s_nop 2
	v_cvt_pk_bf16_f32 v4, v4, v5
	v_cvt_pk_bf16_f32 v5, v6, v7
	global_store_dwordx2 v[46:47], v[4:5], off
	s_waitcnt lgkmcnt(0)
	v_mfma_f32_16x16x16_bf16 v[4:7], v[8:9], v[50:51], 0
	ds_read_b64 v[12:13], v36 offset:3072
	s_waitcnt lgkmcnt(0)
; __device__ __forceinline__ u32x4 pack8(const float* f) { u32x4 w; w.x = cvtpk(f[0], f[1]); w.y = cvtpk(f[2], f[3]); w.z = cvtpk(f[4], f[5]); w.w = cvtpk(f[6], f[7]); return w; }
; __device__ __forceinline__ s16x4 pack4(const f32x4& a) { u32x2 w; w.x = cpk(a.x, a.y); w.y = cpk(a.z, a.w); return __builtin_bit_cast(s16x4, w); }
; __device__ __forceinline__ bf16x8 pack8(const f32x4& a, const f32x4& b) { u32x4 w; w.x = cpk(a.x, a.y); w.y = cpk(a.z, a.w); w.z = cpk(b.x, b.y); w.w = cpk(b.z, b.w); return __builtin_bit_cast(bf16x8, w); }
; __device__ __forceinline__ f32x4 mm16(s16x4 a, s16x4 b, f32x4 c) { f32x4 d = __builtin_amdgcn_mfma_f32_16x16x16bf16_1k(a, b, c, 0, 0, 0); asm volatile("" : "+v"(d) : "v"(a), "v"(b)); return d; }
; #define CHK_LW() asm volatile("s_waitcnt lgkmcnt(0)" ::: "memory")
; __device__ __forceinline__ void precompute(const char* rec, char* out, LAS char* wl, int lane) {
;     ...
; #pragma unroll
;     for (int nk = 0; nk < 4; ++nk) {
;         const s16x4 bcf = CHK_A16(14336, 16 * nk);
;         f32x4 gc[4];
; #pragma unroll
;         for (int mk = 0; mk < 4; ++mk) gc[mk] = mm16(CHK_A16(2560, 16 * mk), bcf, zero4);
;         *(bf16x8*)(out + O_GA + (nk * 2 + 0) * 1024 + lane * 16) = pack8(gc[0], gc[1]);
;         *(bf16x8*)(out + O_GA + (nk * 2 + 1) * 1024 + lane * 16) = pack8(gc[2], gc[3]);
;         f32x4 hc = mm16(CHK_A16(2048, 0), bcf, zero4); hc = mm16(Ident, CHK_A16(6656, 16 * nk), hc);
;         *(s16x4*)(out + O_HA + nk * 512 + lane * 8) = pack4(hc);
;     }
;     CHK_LW();
	v_mfma_f32_16x16x16_bf16 v[8:11], v[12:13], v[50:51], 0
	ds_read_b64 v[16:17], v36 offset:3584
	s_nop 3
	v_cvt_pk_bf16_f32 v4, v4, v5
	s_waitcnt lgkmcnt(0)
	v_mfma_f32_16x16x16_bf16 v[12:15], v[16:17], v[50:51], 0
	ds_read_b64 v[46:47], v36 offset:4096
	v_cvt_pk_bf16_f32 v5, v6, v7
	s_waitcnt lgkmcnt(0)
	v_mfma_f32_16x16x16_bf16 v[16:19], v[46:47], v[50:51], 0
	ds_read_b64 v[46:47], v36 offset:2048
	v_cvt_pk_bf16_f32 v6, v8, v9
	v_cvt_pk_bf16_f32 v7, v10, v11
	global_store_dwordx4 v[48:49], v[4:7], off
	s_nop 1
	v_cvt_pk_bf16_f32 v4, v12, v13
	v_cvt_pk_bf16_f32 v5, v14, v15
	v_cvt_pk_bf16_f32 v6, v16, v17
	v_cvt_pk_bf16_f32 v7, v18, v19
	global_store_dwordx4 v[48:49], v[4:7], off offset:1024
	s_waitcnt lgkmcnt(0)
	s_nop 0
	v_mfma_f32_16x16x16_bf16 v[4:7], v[46:47], v[50:51], 0
	ds_read_b64 v[8:9], v127 offset:6656
	s_waitcnt lgkmcnt(0)
	v_mfma_f32_16x16x16_bf16 v[4:7], v[40:41], v[8:9], v[4:7]
	ds_read_b64 v[8:9], v36 offset:2560
	ds_read_b64 v[46:47], v127 offset:14848
	s_nop 5
	v_cvt_pk_bf16_f32 v4, v4, v5
	v_cvt_pk_bf16_f32 v5, v6, v7
	v_add_co_u32_e32 v6, vcc, s52, v44
	s_nop 1
	v_addc_co_u32_e32 v7, vcc, 0, v45, vcc
	global_store_dwordx2 v[6:7], v[4:5], off offset:2048
	s_waitcnt lgkmcnt(0)
	v_mfma_f32_16x16x16_bf16 v[4:7], v[8:9], v[46:47], 0
	ds_read_b64 v[12:13], v36 offset:3072
	s_waitcnt lgkmcnt(0)
	v_mfma_f32_16x16x16_bf16 v[8:11], v[12:13], v[46:47], 0
	ds_read_b64 v[16:17], v36 offset:3584
	s_nop 3
	v_cvt_pk_bf16_f32 v4, v4, v5
	s_waitcnt lgkmcnt(0)
	v_mfma_f32_16x16x16_bf16 v[12:15], v[16:17], v[46:47], 0
	ds_read_b64 v[50:51], v36 offset:4096
	v_cvt_pk_bf16_f32 v5, v6, v7
	s_waitcnt lgkmcnt(0)
	v_mfma_f32_16x16x16_bf16 v[16:19], v[50:51], v[46:47], 0
	ds_read_b64 v[50:51], v36 offset:2048
	v_cvt_pk_bf16_f32 v6, v8, v9
	v_cvt_pk_bf16_f32 v7, v10, v11
	global_store_dwordx4 v[48:49], v[4:7], off offset:2048
	s_nop 1
	v_cvt_pk_bf16_f32 v4, v12, v13
	v_cvt_pk_bf16_f32 v5, v14, v15
	v_cvt_pk_bf16_f32 v6, v16, v17
	v_cvt_pk_bf16_f32 v7, v18, v19
	global_store_dwordx4 v[48:49], v[4:7], off offset:3072
	v_lshl_add_u64 v[16:17], v[44:45], 0, s[38:39]
	v_add_co_u32_e32 v48, vcc, s51, v48
	s_waitcnt lgkmcnt(0)
	v_mfma_f32_16x16x16_bf16 v[4:7], v[50:51], v[46:47], 0
	ds_read_b64 v[8:9], v127 offset:7168
	v_addc_co_u32_e32 v49, vcc, 0, v49, vcc
	s_waitcnt lgkmcnt(0)
	v_mfma_f32_16x16x16_bf16 v[4:7], v[40:41], v[8:9], v[4:7]
	ds_read_b64 v[8:9], v36 offset:2560
	ds_read_b64 v[18:19], v127 offset:15360
	s_nop 5
	v_cvt_pk_bf16_f32 v4, v4, v5
	v_cvt_pk_bf16_f32 v5, v6, v7
	s_waitcnt lgkmcnt(0)
	v_mfma_f32_16x16x16_bf16 v[12:15], v[8:9], v[18:19], 0
	global_store_dwordx2 v[16:17], v[4:5], off offset:512
	ds_read_b64 v[4:5], v36 offset:3072
	s_waitcnt lgkmcnt(0)
	v_mfma_f32_16x16x16_bf16 v[44:47], v[4:5], v[18:19], 0
	ds_read_b64 v[8:9], v36 offset:3584
	s_nop 2
	v_cvt_pk_bf16_f32 v12, v12, v13
	s_waitcnt lgkmcnt(0)
	v_mfma_f32_16x16x16_bf16 v[4:7], v[8:9], v[18:19], 0
	ds_read_b64 v[50:51], v36 offset:4096
	v_cvt_pk_bf16_f32 v13, v14, v15
	s_waitcnt lgkmcnt(0)
	v_mfma_f32_16x16x16_bf16 v[8:11], v[50:51], v[18:19], 0
	v_cvt_pk_bf16_f32 v14, v44, v45
	ds_read_b64 v[44:45], v36 offset:2048
	s_nop 1
	v_cvt_pk_bf16_f32 v4, v4, v5
	v_cvt_pk_bf16_f32 v5, v6, v7
	s_nop 1
	v_cvt_pk_bf16_f32 v6, v8, v9
	v_cvt_pk_bf16_f32 v7, v10, v11
	v_cvt_pk_bf16_f32 v15, v46, v47
	global_store_dwordx4 v[48:49], v[4:7], off offset:1024
	global_store_dwordx4 v[48:49], v[12:15], off
	s_waitcnt lgkmcnt(0)
	v_mfma_f32_16x16x16_bf16 v[4:7], v[44:45], v[18:19], 0
	ds_read_b64 v[8:9], v127 offset:7680
	s_waitcnt lgkmcnt(0)
	v_mfma_f32_16x16x16_bf16 v[4:7], v[40:41], v[8:9], v[4:7]
	ds_read_b64 v[8:9], v36 offset:2560
	ds_read_b64 v[18:19], v127 offset:15872
	s_nop 5
	v_cvt_pk_bf16_f32 v4, v4, v5
	v_cvt_pk_bf16_f32 v5, v6, v7
	global_store_dwordx2 v[16:17], v[4:5], off offset:1024
	s_waitcnt lgkmcnt(0)
	v_mfma_f32_16x16x16_bf16 v[4:7], v[8:9], v[18:19], 0
	ds_read_b64 v[12:13], v36 offset:3072
	s_waitcnt lgkmcnt(0)
	v_mfma_f32_16x16x16_bf16 v[8:11], v[12:13], v[18:19], 0
	ds_read_b64 v[44:45], v36 offset:3584
	s_nop 3
	v_cvt_pk_bf16_f32 v4, v4, v5
	s_waitcnt lgkmcnt(0)
	v_mfma_f32_16x16x16_bf16 v[12:15], v[44:45], v[18:19], 0
	ds_read_b64 v[50:51], v36 offset:4096
	v_cvt_pk_bf16_f32 v5, v6, v7
	s_waitcnt lgkmcnt(0)
	v_mfma_f32_16x16x16_bf16 v[44:47], v[50:51], v[18:19], 0
	ds_read_b64 v[50:51], v36 offset:2048
	v_cvt_pk_bf16_f32 v6, v8, v9
	v_cvt_pk_bf16_f32 v7, v10, v11
	global_store_dwordx4 v[48:49], v[4:7], off offset:2048
	s_nop 1
	v_cvt_pk_bf16_f32 v4, v12, v13
	v_cvt_pk_bf16_f32 v5, v14, v15
	v_cvt_pk_bf16_f32 v6, v44, v45
	v_cvt_pk_bf16_f32 v7, v46, v47
	global_store_dwordx4 v[48:49], v[4:7], off offset:3072
	s_waitcnt lgkmcnt(0)
	s_nop 0
	v_mfma_f32_16x16x16_bf16 v[4:7], v[50:51], v[18:19], 0
	ds_read_b64 v[8:9], v127 offset:8192
	s_waitcnt lgkmcnt(0)
	v_mfma_f32_16x16x16_bf16 v[4:7], v[40:41], v[8:9], v[4:7]
	s_nop 7
	v_cvt_pk_bf16_f32 v4, v4, v5
	v_cvt_pk_bf16_f32 v5, v6, v7
	global_store_dwordx2 v[16:17], v[4:5], off offset:1536
	s_waitcnt lgkmcnt(0)
	s_cbranch_scc1 .LBB0_677
